# v53 + EpiResid epilogues of P2/P6 re-emitted with packed f32 math, hoisted shuffle indices, counted load waits, deferred row-sum reduction (-230 VALU per wave per tile)
# speedup vs baseline: 1.0038x; 1.0038x over previous
; __device__ __forceinline__ unsigned cvt_pk_bf16(float lo, float hi) { unsigned r; asm volatile("v_cvt_pk_bf16_f32 %0, %1, %2" : "=v"(r) : "v"(lo), "v"(hi)); return r; }
;     __device__ __forceinline__ char* hb_at(const Unit& u, int ai, int m, int bj, int wr, int wc, int fr, int fq) const {
;         return (char*)hb + ((size_t)((u.pm * 16 + u.pn * 4 + bj * 2 + (wc >> 1)) * 2 + ai) * HTB) + lds_byte(wr * 64 + m * 16 + fr, (wc & 1) * 32 + 8 * fq); }
;     __device__ __forceinline__ void operator()(f32x4 (&acc)[2][2][4][2], const Unit& u, int wr, int wc, int fr, int fq) const {
;         const int row0 = u.pm * BM + wr * 64 + fr, col0 = u.pn * BM + wc * 32 + 8 * fq;
;         u32x4 pre[2][4][2];
; #pragma unroll
;         for (int ai = 0; ai < 2; ++ai)
; #pragma unroll
;             for (int m = 0; m < 4; ++m)
; #pragma unroll
;                 for (int bj = 0; bj < 2; ++bj) pre[ai][m][bj] = *(const u32x4*)hb_at(u, ai, m, bj, wr, wc, fr, fq);
; #pragma unroll
;         for (int ai = 0; ai < 2; ++ai)
; #pragma unroll
;             for (int m = 0; m < 4; ++m) { const int row = row0 + ai * HALF + m * 16; float s = 0.f;
; #pragma unroll
;                 for (int bj = 0; bj < 2; ++bj) { const size_t o2 = (size_t)row * 1024 + col0 + bj * HALF; const u32x4 p = pre[ai][m][bj]; const f32x4 a0 = acc[ai][bj][m][0], a1 = acc[ai][bj][m][1];
;                     f32x4 o0, o1; o0[0] = bf_lo(p.x) + a0[0] * alpha; o0[1] = bf_hi(p.x) + a0[1] * alpha; o0[2] = bf_lo(p.y) + a0[2] * alpha; o0[3] = bf_hi(p.y) + a0[3] * alpha;
;                     o1[0] = bf_lo(p.z) + a1[0] * alpha; o1[1] = bf_hi(p.z) + a1[1] * alpha; o1[2] = bf_lo(p.w) + a1[2] * alpha; o1[3] = bf_hi(p.w) + a1[3] * alpha;
;                     s += ((o0[0] * o0[0] + o0[1] * o0[1]) + (o0[2] * o0[2] + o0[3] * o0[3])) + ((o1[0] * o1[0] + o1[1] * o1[1]) + (o1[2] * o1[2] + o1[3] * o1[3]));
;                     u32x4 w; w.x = cvt_pk_bf16(o0[0], o0[1]); w.y = cvt_pk_bf16(o0[2], o0[3]); w.z = cvt_pk_bf16(o1[0], o1[1]); w.w = cvt_pk_bf16(o1[2], o1[3]);
;                     *(u32x4*)hb_at(u, ai, m, bj, wr, wc, fr, fq) = w;
;                     if (out) { *(f32x4*)(out + o2) = o0; *(f32x4*)(out + o2 + 4) = o1; } }
;                 s += __shfl_xor(s, 16); s += __shfl_xor(s, 32);
;                 if (ssq && fq == 0) atomicAdd(ssq + row, s); }
.LBB0_229:
	s_lshl_b32 s8, s72, 3
	s_lshl_b32 s9, s76, 5
	s_add_i32 s9, s9, s8
	s_or_b32 s8, s9, s81
	s_ashr_i32 s9, s8, 31
	s_or_b32 s68, s8, 4
	s_lshl_b64 s[72:73], s[8:9], 14
	s_ashr_i32 s69, s68, 31
	v_lshl_add_u64 v[112:113], v[198:199], 0, s[72:73]
	s_lshl_b64 s[74:75], s[68:69], 14
	global_load_dwordx4 v[220:223], v[112:113], off
	v_lshl_add_u64 v[112:113], v[198:199], 0, s[74:75]
	global_load_dwordx4 v[224:227], v[112:113], off
	s_or_b32 s68, s8, 1
	s_or_b32 s8, s8, 5
	s_ashr_i32 s69, s68, 31
	s_ashr_i32 s9, s8, 31
	s_lshl_b64 s[70:71], s[68:69], 14
	s_lshl_b64 s[68:69], s[8:9], 14
	v_lshl_add_u64 v[112:113], v[200:201], 0, s[72:73]
	v_lshl_add_u64 v[114:115], v[202:203], 0, s[72:73]
	v_lshl_add_u64 v[124:125], v[196:197], 0, s[72:73]
	v_lshl_add_u64 v[126:127], v[200:201], 0, s[74:75]
	v_lshl_add_u64 v[136:137], v[202:203], 0, s[74:75]
	v_lshl_add_u64 v[138:139], v[196:197], 0, s[74:75]
	v_lshl_add_u64 v[140:141], v[198:199], 0, s[70:71]
	v_lshl_add_u64 v[142:143], v[198:199], 0, s[68:69]
	v_lshl_add_u64 v[144:145], v[200:201], 0, s[70:71]
	v_lshl_add_u64 v[146:147], v[200:201], 0, s[68:69]
	v_lshl_add_u64 v[216:217], v[202:203], 0, s[70:71]
	v_lshl_add_u64 v[228:229], v[202:203], 0, s[68:69]
	v_lshl_add_u64 v[230:231], v[196:197], 0, s[70:71]
	v_lshl_add_u64 v[232:233], v[196:197], 0, s[68:69]
	global_load_dwordx4 v[180:183], v[112:113], off
	global_load_dwordx4 v[176:179], v[126:127], off
	global_load_dwordx4 v[172:175], v[114:115], off
	global_load_dwordx4 v[168:171], v[136:137], off
	global_load_dwordx4 v[164:167], v[124:125], off
	global_load_dwordx4 v[160:163], v[138:139], off
	global_load_dwordx4 v[156:159], v[140:141], off
	global_load_dwordx4 v[152:155], v[142:143], off
	global_load_dwordx4 v[148:151], v[144:145], off
	s_nop 0
	global_load_dwordx4 v[144:147], v[146:147], off
	s_nop 0
	global_load_dwordx4 v[140:143], v[216:217], off
	global_load_dwordx4 v[136:139], v[228:229], off
	global_load_dwordx4 v[124:127], v[230:231], off
	global_load_dwordx4 v[112:115], v[232:233], off
	v_lshl_add_u32 v208, s76, 8, v189
	v_readlane_b32 s99, v246, 6
	s_nop 1
	s_cmp_lt_u32 s99, 4
	s_cbranch_scc0 .Lnoal_1
	s_barrier
.Lnoal_1:
	v_ashrrev_i32_e32 v209, 31, v208
	v_lshl_add_u64 v[250:251], v[208:209], 2, s[10:11]
	v_xor_b32_e32 v247, 16, v215
	v_xor_b32_e32 v248, 32, v215
	v_lshlrev_b32_e32 v247, 2, v247
	v_lshlrev_b32_e32 v248, 2, v248
	s_mov_b32 s100, 0.5
	s_mov_b32 s101, 0.5
	s_waitcnt vmcnt(15)
	v_lshlrev_b32_e32 v216, 16, v220
	v_and_b32_e32 v217, 0xffff0000, v220
	v_lshlrev_b32_e32 v228, 16, v221
	v_and_b32_e32 v229, 0xffff0000, v221
	v_lshlrev_b32_e32 v230, 16, v222
	v_and_b32_e32 v231, 0xffff0000, v222
	v_lshlrev_b32_e32 v232, 16, v223
	v_and_b32_e32 v233, 0xffff0000, v223
	v_pk_fma_f32 v[132:133], v[132:133], s[100:101], v[216:217]
	v_pk_fma_f32 v[134:135], v[134:135], s[100:101], v[228:229]
	v_pk_fma_f32 v[128:129], v[128:129], s[100:101], v[230:231]
	v_pk_fma_f32 v[130:131], v[130:131], s[100:101], v[232:233]
	s_waitcnt vmcnt(14)
	v_lshlrev_b32_e32 v220, 16, v224
	v_and_b32_e32 v221, 0xffff0000, v224
	v_lshlrev_b32_e32 v222, 16, v225
	v_and_b32_e32 v223, 0xffff0000, v225
	v_lshlrev_b32_e32 v254, 16, v226
	v_and_b32_e32 v255, 0xffff0000, v226
	v_lshlrev_b32_e32 v226, 16, v227
	v_and_b32_e32 v227, 0xffff0000, v227
	v_pk_fma_f32 v[120:121], v[120:121], s[100:101], v[220:221]
	v_pk_fma_f32 v[122:123], v[122:123], s[100:101], v[222:223]
	v_pk_fma_f32 v[116:117], v[116:117], s[100:101], v[254:255]
	v_pk_fma_f32 v[118:119], v[118:119], s[100:101], v[226:227]
	v_pk_mul_f32 v[216:217], v[132:133], v[132:133]
	v_pk_mul_f32 v[228:229], v[120:121], v[120:121]
	v_pk_fma_f32 v[216:217], v[134:135], v[134:135], v[216:217]
	v_pk_fma_f32 v[228:229], v[122:123], v[122:123], v[228:229]
	v_pk_fma_f32 v[216:217], v[128:129], v[128:129], v[216:217]
	v_pk_fma_f32 v[228:229], v[116:117], v[116:117], v[228:229]
	v_pk_fma_f32 v[216:217], v[130:131], v[130:131], v[216:217]
	v_pk_fma_f32 v[228:229], v[118:119], v[118:119], v[228:229]
	v_pk_add_f32 v[216:217], v[216:217], v[228:229]
	v_cvt_pk_bf16_f32 v220, v132, v133
	v_cvt_pk_bf16_f32 v221, v134, v135
	v_cvt_pk_bf16_f32 v222, v128, v129
	v_cvt_pk_bf16_f32 v223, v130, v131
	v_lshl_add_u64 v[232:233], v[198:199], 0, s[72:73]
	global_store_dwordx4 v[232:233], v[220:223], off sc1
	v_add_f32_e32 v249, v216, v217
	v_cvt_pk_bf16_f32 v224, v120, v121
	v_cvt_pk_bf16_f32 v225, v122, v123
	v_cvt_pk_bf16_f32 v226, v116, v117
	v_cvt_pk_bf16_f32 v227, v118, v119
	ds_bpermute_b32 v253, v247, v249
	v_lshl_add_u64 v[230:231], v[198:199], 0, s[74:75]
	global_store_dwordx4 v[230:231], v[224:227], off sc1
	s_waitcnt vmcnt(15)
	v_lshlrev_b32_e32 v216, 16, v180
	v_and_b32_e32 v217, 0xffff0000, v180
	v_lshlrev_b32_e32 v228, 16, v181
	v_and_b32_e32 v229, 0xffff0000, v181
	v_lshlrev_b32_e32 v230, 16, v182
	v_and_b32_e32 v231, 0xffff0000, v182
	v_lshlrev_b32_e32 v232, 16, v183
	v_and_b32_e32 v233, 0xffff0000, v183
	v_pk_fma_f32 v[108:109], v[108:109], s[100:101], v[216:217]
	v_pk_fma_f32 v[110:111], v[110:111], s[100:101], v[228:229]
	v_pk_fma_f32 v[104:105], v[104:105], s[100:101], v[230:231]
	v_pk_fma_f32 v[106:107], v[106:107], s[100:101], v[232:233]
	s_waitcnt lgkmcnt(0)
	v_add_f32_e32 v249, v249, v253
	ds_bpermute_b32 v253, v248, v249
	s_waitcnt vmcnt(14)
	v_lshlrev_b32_e32 v180, 16, v176
	v_and_b32_e32 v181, 0xffff0000, v176
	v_lshlrev_b32_e32 v182, 16, v177
	v_and_b32_e32 v183, 0xffff0000, v177
	v_lshlrev_b32_e32 v254, 16, v178
	v_and_b32_e32 v255, 0xffff0000, v178
	v_lshlrev_b32_e32 v178, 16, v179
	v_and_b32_e32 v179, 0xffff0000, v179
	v_pk_fma_f32 v[100:101], v[100:101], s[100:101], v[180:181]
	v_pk_fma_f32 v[102:103], v[102:103], s[100:101], v[182:183]
	v_pk_fma_f32 v[96:97], v[96:97], s[100:101], v[254:255]
	v_pk_fma_f32 v[98:99], v[98:99], s[100:101], v[178:179]
	s_waitcnt lgkmcnt(0)
; __device__ __forceinline__ unsigned cvt_pk_bf16(float lo, float hi) { unsigned r; asm volatile("v_cvt_pk_bf16_f32 %0, %1, %2" : "=v"(r) : "v"(lo), "v"(hi)); return r; }
; __device__ __forceinline__ float bf_lo(unsigned w) { return __uint_as_float(w << 16); }
; __device__ __forceinline__ float bf_hi(unsigned w) { return __uint_as_float(w & 0xffff0000u); }
;     __device__ __forceinline__ void operator()(f32x4 (&acc)[2][2][4][2], const Unit& u, int wr, int wc, int fr, int fq) const {
;     ...
;             for (int m = 0; m < 4; ++m) { const int row = row0 + ai * HALF + m * 16; float s = 0.f;
; #pragma unroll
;                 for (int bj = 0; bj < 2; ++bj) { const size_t o2 = (size_t)row * 1024 + col0 + bj * HALF; const u32x4 p = pre[ai][m][bj]; const f32x4 a0 = acc[ai][bj][m][0], a1 = acc[ai][bj][m][1];
;                     f32x4 o0, o1; o0[0] = bf_lo(p.x) + a0[0] * alpha; o0[1] = bf_hi(p.x) + a0[1] * alpha; o0[2] = bf_lo(p.y) + a0[2] * alpha; o0[3] = bf_hi(p.y) + a0[3] * alpha;
;                     o1[0] = bf_lo(p.z) + a1[0] * alpha; o1[1] = bf_hi(p.z) + a1[1] * alpha; o1[2] = bf_lo(p.w) + a1[2] * alpha; o1[3] = bf_hi(p.w) + a1[3] * alpha;
;                     s += ((o0[0] * o0[0] + o0[1] * o0[1]) + (o0[2] * o0[2] + o0[3] * o0[3])) + ((o1[0] * o1[0] + o1[1] * o1[1]) + (o1[2] * o1[2] + o1[3] * o1[3]));
;                     u32x4 w; w.x = cvt_pk_bf16(o0[0], o0[1]); w.y = cvt_pk_bf16(o0[2], o0[3]); w.z = cvt_pk_bf16(o1[0], o1[1]); w.w = cvt_pk_bf16(o1[2], o1[3]);
;                     *(u32x4*)hb_at(u, ai, m, bj, wr, wc, fr, fq) = w;
;                     if (out) { *(f32x4*)(out + o2) = o0; *(f32x4*)(out + o2 + 4) = o1; } }
;                 s += __shfl_xor(s, 16); s += __shfl_xor(s, 32);
;                 if (ssq && fq == 0) atomicAdd(ssq + row, s); }
	v_add_f32_e32 v249, v249, v253
	s_and_saveexec_b64 s[98:99], s[2:3]
	global_atomic_add_f32 v[250:251], v249, off
	s_or_b64 exec, exec, s[98:99]
	v_pk_mul_f32 v[216:217], v[108:109], v[108:109]
	v_pk_mul_f32 v[228:229], v[100:101], v[100:101]
	v_pk_fma_f32 v[216:217], v[110:111], v[110:111], v[216:217]
	v_pk_fma_f32 v[228:229], v[102:103], v[102:103], v[228:229]
	v_pk_fma_f32 v[216:217], v[104:105], v[104:105], v[216:217]
	v_pk_fma_f32 v[228:229], v[96:97], v[96:97], v[228:229]
	v_pk_fma_f32 v[216:217], v[106:107], v[106:107], v[216:217]
	v_pk_fma_f32 v[228:229], v[98:99], v[98:99], v[228:229]
	v_pk_add_f32 v[216:217], v[216:217], v[228:229]
	v_cvt_pk_bf16_f32 v180, v108, v109
	v_cvt_pk_bf16_f32 v181, v110, v111
	v_cvt_pk_bf16_f32 v182, v104, v105
	v_cvt_pk_bf16_f32 v183, v106, v107
	v_lshl_add_u64 v[232:233], v[200:201], 0, s[72:73]
	global_store_dwordx4 v[232:233], v[180:183], off sc1
	v_add_f32_e32 v252, v216, v217
	v_cvt_pk_bf16_f32 v176, v100, v101
	v_cvt_pk_bf16_f32 v177, v102, v103
	v_cvt_pk_bf16_f32 v178, v96, v97
	v_cvt_pk_bf16_f32 v179, v98, v99
	ds_bpermute_b32 v253, v247, v252
	v_lshl_add_u64 v[230:231], v[200:201], 0, s[74:75]
	global_store_dwordx4 v[230:231], v[176:179], off sc1
	s_waitcnt vmcnt(15)
	v_lshlrev_b32_e32 v216, 16, v172
	v_and_b32_e32 v217, 0xffff0000, v172
	v_lshlrev_b32_e32 v228, 16, v173
	v_and_b32_e32 v229, 0xffff0000, v173
	v_lshlrev_b32_e32 v230, 16, v174
	v_and_b32_e32 v231, 0xffff0000, v174
	v_lshlrev_b32_e32 v232, 16, v175
	v_and_b32_e32 v233, 0xffff0000, v175
	v_pk_fma_f32 v[92:93], v[92:93], s[100:101], v[216:217]
	v_pk_fma_f32 v[94:95], v[94:95], s[100:101], v[228:229]
	v_pk_fma_f32 v[88:89], v[88:89], s[100:101], v[230:231]
	v_pk_fma_f32 v[90:91], v[90:91], s[100:101], v[232:233]
	s_waitcnt lgkmcnt(0)
	v_add_f32_e32 v252, v252, v253
	ds_bpermute_b32 v253, v248, v252
	s_waitcnt vmcnt(14)
	v_lshlrev_b32_e32 v172, 16, v168
	v_and_b32_e32 v173, 0xffff0000, v168
	v_lshlrev_b32_e32 v174, 16, v169
	v_and_b32_e32 v175, 0xffff0000, v169
	v_lshlrev_b32_e32 v254, 16, v170
	v_and_b32_e32 v255, 0xffff0000, v170
	v_lshlrev_b32_e32 v170, 16, v171
	v_and_b32_e32 v171, 0xffff0000, v171
	v_pk_fma_f32 v[84:85], v[84:85], s[100:101], v[172:173]
	v_pk_fma_f32 v[86:87], v[86:87], s[100:101], v[174:175]
	v_pk_fma_f32 v[80:81], v[80:81], s[100:101], v[254:255]
	v_pk_fma_f32 v[82:83], v[82:83], s[100:101], v[170:171]
	s_waitcnt lgkmcnt(0)
	v_add_f32_e32 v252, v252, v253
	s_and_saveexec_b64 s[98:99], s[2:3]
	global_atomic_add_f32 v[250:251], v252, off offset:64
	s_or_b64 exec, exec, s[98:99]
	v_pk_mul_f32 v[216:217], v[92:93], v[92:93]
	v_pk_mul_f32 v[228:229], v[84:85], v[84:85]
	v_pk_fma_f32 v[216:217], v[94:95], v[94:95], v[216:217]
	v_pk_fma_f32 v[228:229], v[86:87], v[86:87], v[228:229]
	v_pk_fma_f32 v[216:217], v[88:89], v[88:89], v[216:217]
	v_pk_fma_f32 v[228:229], v[80:81], v[80:81], v[228:229]
	v_pk_fma_f32 v[216:217], v[90:91], v[90:91], v[216:217]
	v_pk_fma_f32 v[228:229], v[82:83], v[82:83], v[228:229]
	v_pk_add_f32 v[216:217], v[216:217], v[228:229]
	v_cvt_pk_bf16_f32 v172, v92, v93
	v_cvt_pk_bf16_f32 v173, v94, v95
	v_cvt_pk_bf16_f32 v174, v88, v89
	v_cvt_pk_bf16_f32 v175, v90, v91
	v_lshl_add_u64 v[232:233], v[202:203], 0, s[72:73]
	global_store_dwordx4 v[232:233], v[172:175], off sc1
	v_add_f32_e32 v249, v216, v217
	v_cvt_pk_bf16_f32 v168, v84, v85
	v_cvt_pk_bf16_f32 v169, v86, v87
	v_cvt_pk_bf16_f32 v170, v80, v81
	v_cvt_pk_bf16_f32 v171, v82, v83
	ds_bpermute_b32 v253, v247, v249
	v_lshl_add_u64 v[230:231], v[202:203], 0, s[74:75]
	global_store_dwordx4 v[230:231], v[168:171], off sc1
	s_waitcnt vmcnt(15)
	v_lshlrev_b32_e32 v216, 16, v164
	v_and_b32_e32 v217, 0xffff0000, v164
	v_lshlrev_b32_e32 v228, 16, v165
	v_and_b32_e32 v229, 0xffff0000, v165
	v_lshlrev_b32_e32 v230, 16, v166
	v_and_b32_e32 v231, 0xffff0000, v166
	v_lshlrev_b32_e32 v232, 16, v167
	v_and_b32_e32 v233, 0xffff0000, v167
	v_pk_fma_f32 v[76:77], v[76:77], s[100:101], v[216:217]
	v_pk_fma_f32 v[78:79], v[78:79], s[100:101], v[228:229]
	v_pk_fma_f32 v[72:73], v[72:73], s[100:101], v[230:231]
	v_pk_fma_f32 v[74:75], v[74:75], s[100:101], v[232:233]
	s_waitcnt lgkmcnt(0)
	v_add_f32_e32 v249, v249, v253
	ds_bpermute_b32 v253, v248, v249
	s_waitcnt vmcnt(14)
	v_lshlrev_b32_e32 v164, 16, v160
	v_and_b32_e32 v165, 0xffff0000, v160
	v_lshlrev_b32_e32 v166, 16, v161
	v_and_b32_e32 v167, 0xffff0000, v161
	v_lshlrev_b32_e32 v254, 16, v162
	v_and_b32_e32 v255, 0xffff0000, v162
	v_lshlrev_b32_e32 v162, 16, v163
	v_and_b32_e32 v163, 0xffff0000, v163
	v_pk_fma_f32 v[68:69], v[68:69], s[100:101], v[164:165]
	v_pk_fma_f32 v[70:71], v[70:71], s[100:101], v[166:167]
	v_pk_fma_f32 v[64:65], v[64:65], s[100:101], v[254:255]
	v_pk_fma_f32 v[66:67], v[66:67], s[100:101], v[162:163]
	s_waitcnt lgkmcnt(0)
	v_add_f32_e32 v249, v249, v253
	s_and_saveexec_b64 s[98:99], s[2:3]
	global_atomic_add_f32 v[250:251], v249, off offset:128
	s_or_b64 exec, exec, s[98:99]
	v_pk_mul_f32 v[216:217], v[76:77], v[76:77]
	v_pk_mul_f32 v[228:229], v[68:69], v[68:69]
	v_pk_fma_f32 v[216:217], v[78:79], v[78:79], v[216:217]
	v_pk_fma_f32 v[228:229], v[70:71], v[70:71], v[228:229]
	v_pk_fma_f32 v[216:217], v[72:73], v[72:73], v[216:217]
	v_pk_fma_f32 v[228:229], v[64:65], v[64:65], v[228:229]
	v_pk_fma_f32 v[216:217], v[74:75], v[74:75], v[216:217]
	v_pk_fma_f32 v[228:229], v[66:67], v[66:67], v[228:229]
	v_pk_add_f32 v[216:217], v[216:217], v[228:229]
	v_cvt_pk_bf16_f32 v164, v76, v77
	v_cvt_pk_bf16_f32 v165, v78, v79
	v_cvt_pk_bf16_f32 v166, v72, v73
	v_cvt_pk_bf16_f32 v167, v74, v75
	v_lshl_add_u64 v[232:233], v[196:197], 0, s[72:73]
	global_store_dwordx4 v[232:233], v[164:167], off sc1
	v_add_f32_e32 v252, v216, v217
	v_cvt_pk_bf16_f32 v160, v68, v69
	v_cvt_pk_bf16_f32 v161, v70, v71
	v_cvt_pk_bf16_f32 v162, v64, v65
	v_cvt_pk_bf16_f32 v163, v66, v67
	ds_bpermute_b32 v253, v247, v252
	v_lshl_add_u64 v[230:231], v[196:197], 0, s[74:75]
	global_store_dwordx4 v[230:231], v[160:163], off sc1
	s_waitcnt vmcnt(15)
; __device__ __forceinline__ unsigned cvt_pk_bf16(float lo, float hi) { unsigned r; asm volatile("v_cvt_pk_bf16_f32 %0, %1, %2" : "=v"(r) : "v"(lo), "v"(hi)); return r; }
; __device__ __forceinline__ float bf_lo(unsigned w) { return __uint_as_float(w << 16); }
; __device__ __forceinline__ float bf_hi(unsigned w) { return __uint_as_float(w & 0xffff0000u); }
;     __device__ __forceinline__ void operator()(f32x4 (&acc)[2][2][4][2], const Unit& u, int wr, int wc, int fr, int fq) const {
;     ...
;             for (int m = 0; m < 4; ++m) { const int row = row0 + ai * HALF + m * 16; float s = 0.f;
; #pragma unroll
;                 for (int bj = 0; bj < 2; ++bj) { const size_t o2 = (size_t)row * 1024 + col0 + bj * HALF; const u32x4 p = pre[ai][m][bj]; const f32x4 a0 = acc[ai][bj][m][0], a1 = acc[ai][bj][m][1];
;                     f32x4 o0, o1; o0[0] = bf_lo(p.x) + a0[0] * alpha; o0[1] = bf_hi(p.x) + a0[1] * alpha; o0[2] = bf_lo(p.y) + a0[2] * alpha; o0[3] = bf_hi(p.y) + a0[3] * alpha;
;                     o1[0] = bf_lo(p.z) + a1[0] * alpha; o1[1] = bf_hi(p.z) + a1[1] * alpha; o1[2] = bf_lo(p.w) + a1[2] * alpha; o1[3] = bf_hi(p.w) + a1[3] * alpha;
;                     s += ((o0[0] * o0[0] + o0[1] * o0[1]) + (o0[2] * o0[2] + o0[3] * o0[3])) + ((o1[0] * o1[0] + o1[1] * o1[1]) + (o1[2] * o1[2] + o1[3] * o1[3]));
;                     u32x4 w; w.x = cvt_pk_bf16(o0[0], o0[1]); w.y = cvt_pk_bf16(o0[2], o0[3]); w.z = cvt_pk_bf16(o1[0], o1[1]); w.w = cvt_pk_bf16(o1[2], o1[3]);
;                     *(u32x4*)hb_at(u, ai, m, bj, wr, wc, fr, fq) = w;
;                     if (out) { *(f32x4*)(out + o2) = o0; *(f32x4*)(out + o2 + 4) = o1; } }
;                 s += __shfl_xor(s, 16); s += __shfl_xor(s, 32);
;                 if (ssq && fq == 0) atomicAdd(ssq + row, s); }
	v_lshlrev_b32_e32 v216, 16, v156
	v_and_b32_e32 v217, 0xffff0000, v156
	v_lshlrev_b32_e32 v228, 16, v157
	v_and_b32_e32 v229, 0xffff0000, v157
	v_lshlrev_b32_e32 v230, 16, v158
	v_and_b32_e32 v231, 0xffff0000, v158
	v_lshlrev_b32_e32 v232, 16, v159
	v_and_b32_e32 v233, 0xffff0000, v159
	v_pk_fma_f32 v[60:61], v[60:61], s[100:101], v[216:217]
	v_pk_fma_f32 v[62:63], v[62:63], s[100:101], v[228:229]
	v_pk_fma_f32 v[56:57], v[56:57], s[100:101], v[230:231]
	v_pk_fma_f32 v[58:59], v[58:59], s[100:101], v[232:233]
	s_waitcnt lgkmcnt(0)
	v_add_f32_e32 v252, v252, v253
	ds_bpermute_b32 v253, v248, v252
	s_waitcnt vmcnt(14)
	v_lshlrev_b32_e32 v156, 16, v152
	v_and_b32_e32 v157, 0xffff0000, v152
	v_lshlrev_b32_e32 v158, 16, v153
	v_and_b32_e32 v159, 0xffff0000, v153
	v_lshlrev_b32_e32 v254, 16, v154
	v_and_b32_e32 v255, 0xffff0000, v154
	v_lshlrev_b32_e32 v154, 16, v155
	v_and_b32_e32 v155, 0xffff0000, v155
	v_pk_fma_f32 v[52:53], v[52:53], s[100:101], v[156:157]
	v_pk_fma_f32 v[54:55], v[54:55], s[100:101], v[158:159]
	v_pk_fma_f32 v[48:49], v[48:49], s[100:101], v[254:255]
	v_pk_fma_f32 v[50:51], v[50:51], s[100:101], v[154:155]
	s_waitcnt lgkmcnt(0)
	v_add_f32_e32 v252, v252, v253
	s_and_saveexec_b64 s[98:99], s[2:3]
	global_atomic_add_f32 v[250:251], v252, off offset:192
	s_or_b64 exec, exec, s[98:99]
	v_pk_mul_f32 v[216:217], v[60:61], v[60:61]
	v_pk_mul_f32 v[228:229], v[52:53], v[52:53]
	v_pk_fma_f32 v[216:217], v[62:63], v[62:63], v[216:217]
	v_pk_fma_f32 v[228:229], v[54:55], v[54:55], v[228:229]
	v_pk_fma_f32 v[216:217], v[56:57], v[56:57], v[216:217]
	v_pk_fma_f32 v[228:229], v[48:49], v[48:49], v[228:229]
	v_pk_fma_f32 v[216:217], v[58:59], v[58:59], v[216:217]
	v_pk_fma_f32 v[228:229], v[50:51], v[50:51], v[228:229]
	v_pk_add_f32 v[216:217], v[216:217], v[228:229]
	v_cvt_pk_bf16_f32 v156, v60, v61
	v_cvt_pk_bf16_f32 v157, v62, v63
	v_cvt_pk_bf16_f32 v158, v56, v57
	v_cvt_pk_bf16_f32 v159, v58, v59
	v_lshl_add_u64 v[232:233], v[198:199], 0, s[70:71]
	global_store_dwordx4 v[232:233], v[156:159], off sc1
	v_add_f32_e32 v249, v216, v217
	v_cvt_pk_bf16_f32 v152, v52, v53
	v_cvt_pk_bf16_f32 v153, v54, v55
	v_cvt_pk_bf16_f32 v154, v48, v49
	v_cvt_pk_bf16_f32 v155, v50, v51
	ds_bpermute_b32 v253, v247, v249
	v_lshl_add_u64 v[230:231], v[198:199], 0, s[68:69]
	global_store_dwordx4 v[230:231], v[152:155], off sc1
	s_waitcnt vmcnt(15)
	v_lshlrev_b32_e32 v216, 16, v148
	v_and_b32_e32 v217, 0xffff0000, v148
	v_lshlrev_b32_e32 v228, 16, v149
	v_and_b32_e32 v229, 0xffff0000, v149
	v_lshlrev_b32_e32 v230, 16, v150
	v_and_b32_e32 v231, 0xffff0000, v150
	v_lshlrev_b32_e32 v232, 16, v151
	v_and_b32_e32 v233, 0xffff0000, v151
	v_pk_fma_f32 v[44:45], v[44:45], s[100:101], v[216:217]
	v_pk_fma_f32 v[46:47], v[46:47], s[100:101], v[228:229]
	v_pk_fma_f32 v[40:41], v[40:41], s[100:101], v[230:231]
	v_pk_fma_f32 v[42:43], v[42:43], s[100:101], v[232:233]
	s_waitcnt lgkmcnt(0)
	v_add_f32_e32 v249, v249, v253
	ds_bpermute_b32 v253, v248, v249
	s_waitcnt vmcnt(14)
	v_lshlrev_b32_e32 v148, 16, v144
	v_and_b32_e32 v149, 0xffff0000, v144
	v_lshlrev_b32_e32 v150, 16, v145
	v_and_b32_e32 v151, 0xffff0000, v145
	v_lshlrev_b32_e32 v254, 16, v146
	v_and_b32_e32 v255, 0xffff0000, v146
	v_lshlrev_b32_e32 v146, 16, v147
	v_and_b32_e32 v147, 0xffff0000, v147
	v_pk_fma_f32 v[36:37], v[36:37], s[100:101], v[148:149]
	v_pk_fma_f32 v[38:39], v[38:39], s[100:101], v[150:151]
	v_pk_fma_f32 v[32:33], v[32:33], s[100:101], v[254:255]
	v_pk_fma_f32 v[34:35], v[34:35], s[100:101], v[146:147]
	s_waitcnt lgkmcnt(0)
	v_add_f32_e32 v249, v249, v253
	s_and_saveexec_b64 s[98:99], s[2:3]
	global_atomic_add_f32 v[250:251], v249, off offset:512
	s_or_b64 exec, exec, s[98:99]
	v_pk_mul_f32 v[216:217], v[44:45], v[44:45]
	v_pk_mul_f32 v[228:229], v[36:37], v[36:37]
	v_pk_fma_f32 v[216:217], v[46:47], v[46:47], v[216:217]
	v_pk_fma_f32 v[228:229], v[38:39], v[38:39], v[228:229]
	v_pk_fma_f32 v[216:217], v[40:41], v[40:41], v[216:217]
	v_pk_fma_f32 v[228:229], v[32:33], v[32:33], v[228:229]
	v_pk_fma_f32 v[216:217], v[42:43], v[42:43], v[216:217]
	v_pk_fma_f32 v[228:229], v[34:35], v[34:35], v[228:229]
	v_pk_add_f32 v[216:217], v[216:217], v[228:229]
	v_cvt_pk_bf16_f32 v148, v44, v45
	v_cvt_pk_bf16_f32 v149, v46, v47
	v_cvt_pk_bf16_f32 v150, v40, v41
	v_cvt_pk_bf16_f32 v151, v42, v43
	v_lshl_add_u64 v[232:233], v[200:201], 0, s[70:71]
	global_store_dwordx4 v[232:233], v[148:151], off sc1
	v_add_f32_e32 v252, v216, v217
	v_cvt_pk_bf16_f32 v144, v36, v37
	v_cvt_pk_bf16_f32 v145, v38, v39
	v_cvt_pk_bf16_f32 v146, v32, v33
	v_cvt_pk_bf16_f32 v147, v34, v35
	ds_bpermute_b32 v253, v247, v252
	v_lshl_add_u64 v[230:231], v[200:201], 0, s[68:69]
	global_store_dwordx4 v[230:231], v[144:147], off sc1
	s_waitcnt vmcnt(15)
; __device__ __forceinline__ unsigned cvt_pk_bf16(float lo, float hi) { unsigned r; asm volatile("v_cvt_pk_bf16_f32 %0, %1, %2" : "=v"(r) : "v"(lo), "v"(hi)); return r; }
; __device__ __forceinline__ float bf_lo(unsigned w) { return __uint_as_float(w << 16); }
; __device__ __forceinline__ float bf_hi(unsigned w) { return __uint_as_float(w & 0xffff0000u); }
;     __device__ __forceinline__ void operator()(f32x4 (&acc)[2][2][4][2], const Unit& u, int wr, int wc, int fr, int fq) const {
;     ...
;             for (int m = 0; m < 4; ++m) { const int row = row0 + ai * HALF + m * 16; float s = 0.f;
; #pragma unroll
;                 for (int bj = 0; bj < 2; ++bj) { const size_t o2 = (size_t)row * 1024 + col0 + bj * HALF; const u32x4 p = pre[ai][m][bj]; const f32x4 a0 = acc[ai][bj][m][0], a1 = acc[ai][bj][m][1];
;                     f32x4 o0, o1; o0[0] = bf_lo(p.x) + a0[0] * alpha; o0[1] = bf_hi(p.x) + a0[1] * alpha; o0[2] = bf_lo(p.y) + a0[2] * alpha; o0[3] = bf_hi(p.y) + a0[3] * alpha;
;                     o1[0] = bf_lo(p.z) + a1[0] * alpha; o1[1] = bf_hi(p.z) + a1[1] * alpha; o1[2] = bf_lo(p.w) + a1[2] * alpha; o1[3] = bf_hi(p.w) + a1[3] * alpha;
;                     s += ((o0[0] * o0[0] + o0[1] * o0[1]) + (o0[2] * o0[2] + o0[3] * o0[3])) + ((o1[0] * o1[0] + o1[1] * o1[1]) + (o1[2] * o1[2] + o1[3] * o1[3]));
;                     u32x4 w; w.x = cvt_pk_bf16(o0[0], o0[1]); w.y = cvt_pk_bf16(o0[2], o0[3]); w.z = cvt_pk_bf16(o1[0], o1[1]); w.w = cvt_pk_bf16(o1[2], o1[3]);
;                     *(u32x4*)hb_at(u, ai, m, bj, wr, wc, fr, fq) = w;
;                     if (out) { *(f32x4*)(out + o2) = o0; *(f32x4*)(out + o2 + 4) = o1; } }
;                 s += __shfl_xor(s, 16); s += __shfl_xor(s, 32);
;                 if (ssq && fq == 0) atomicAdd(ssq + row, s); }
	v_lshlrev_b32_e32 v216, 16, v140
	v_and_b32_e32 v217, 0xffff0000, v140
	v_lshlrev_b32_e32 v228, 16, v141
	v_and_b32_e32 v229, 0xffff0000, v141
	v_lshlrev_b32_e32 v230, 16, v142
	v_and_b32_e32 v231, 0xffff0000, v142
	v_lshlrev_b32_e32 v232, 16, v143
	v_and_b32_e32 v233, 0xffff0000, v143
	v_pk_fma_f32 v[28:29], v[28:29], s[100:101], v[216:217]
	v_pk_fma_f32 v[30:31], v[30:31], s[100:101], v[228:229]
	v_pk_fma_f32 v[24:25], v[24:25], s[100:101], v[230:231]
	v_pk_fma_f32 v[26:27], v[26:27], s[100:101], v[232:233]
	s_waitcnt lgkmcnt(0)
	v_add_f32_e32 v252, v252, v253
	ds_bpermute_b32 v253, v248, v252
	s_waitcnt vmcnt(14)
	v_lshlrev_b32_e32 v140, 16, v136
	v_and_b32_e32 v141, 0xffff0000, v136
	v_lshlrev_b32_e32 v142, 16, v137
	v_and_b32_e32 v143, 0xffff0000, v137
	v_lshlrev_b32_e32 v254, 16, v138
	v_and_b32_e32 v255, 0xffff0000, v138
	v_lshlrev_b32_e32 v138, 16, v139
	v_and_b32_e32 v139, 0xffff0000, v139
	v_pk_fma_f32 v[20:21], v[20:21], s[100:101], v[140:141]
	v_pk_fma_f32 v[22:23], v[22:23], s[100:101], v[142:143]
	v_pk_fma_f32 v[16:17], v[16:17], s[100:101], v[254:255]
	v_pk_fma_f32 v[18:19], v[18:19], s[100:101], v[138:139]
	s_waitcnt lgkmcnt(0)
	v_add_f32_e32 v252, v252, v253
	s_and_saveexec_b64 s[98:99], s[2:3]
	global_atomic_add_f32 v[250:251], v252, off offset:576
	s_or_b64 exec, exec, s[98:99]
	v_pk_mul_f32 v[216:217], v[28:29], v[28:29]
	v_pk_mul_f32 v[228:229], v[20:21], v[20:21]
	v_pk_fma_f32 v[216:217], v[30:31], v[30:31], v[216:217]
	v_pk_fma_f32 v[228:229], v[22:23], v[22:23], v[228:229]
	v_pk_fma_f32 v[216:217], v[24:25], v[24:25], v[216:217]
	v_pk_fma_f32 v[228:229], v[16:17], v[16:17], v[228:229]
	v_pk_fma_f32 v[216:217], v[26:27], v[26:27], v[216:217]
	v_pk_fma_f32 v[228:229], v[18:19], v[18:19], v[228:229]
	v_pk_add_f32 v[216:217], v[216:217], v[228:229]
	v_cvt_pk_bf16_f32 v140, v28, v29
	v_cvt_pk_bf16_f32 v141, v30, v31
	v_cvt_pk_bf16_f32 v142, v24, v25
	v_cvt_pk_bf16_f32 v143, v26, v27
	v_lshl_add_u64 v[232:233], v[202:203], 0, s[70:71]
	global_store_dwordx4 v[232:233], v[140:143], off sc1
	v_add_f32_e32 v249, v216, v217
	v_cvt_pk_bf16_f32 v136, v20, v21
	v_cvt_pk_bf16_f32 v137, v22, v23
	v_cvt_pk_bf16_f32 v138, v16, v17
	v_cvt_pk_bf16_f32 v139, v18, v19
	ds_bpermute_b32 v253, v247, v249
	v_lshl_add_u64 v[230:231], v[202:203], 0, s[68:69]
	global_store_dwordx4 v[230:231], v[136:139], off sc1
	s_waitcnt vmcnt(15)
	v_lshlrev_b32_e32 v216, 16, v124
	v_and_b32_e32 v217, 0xffff0000, v124
	v_lshlrev_b32_e32 v228, 16, v125
	v_and_b32_e32 v229, 0xffff0000, v125
	v_lshlrev_b32_e32 v230, 16, v126
	v_and_b32_e32 v231, 0xffff0000, v126
	v_lshlrev_b32_e32 v232, 16, v127
	v_and_b32_e32 v233, 0xffff0000, v127
	v_pk_fma_f32 v[12:13], v[12:13], s[100:101], v[216:217]
	v_pk_fma_f32 v[14:15], v[14:15], s[100:101], v[228:229]
	v_pk_fma_f32 v[8:9], v[8:9], s[100:101], v[230:231]
	v_pk_fma_f32 v[10:11], v[10:11], s[100:101], v[232:233]
	s_waitcnt lgkmcnt(0)
	v_add_f32_e32 v249, v249, v253
	ds_bpermute_b32 v253, v248, v249
	s_waitcnt vmcnt(14)
	v_lshlrev_b32_e32 v124, 16, v112
	v_and_b32_e32 v125, 0xffff0000, v112
	v_lshlrev_b32_e32 v126, 16, v113
	v_and_b32_e32 v127, 0xffff0000, v113
	v_lshlrev_b32_e32 v254, 16, v114
	v_and_b32_e32 v255, 0xffff0000, v114
	v_lshlrev_b32_e32 v114, 16, v115
	v_and_b32_e32 v115, 0xffff0000, v115
	v_pk_fma_f32 v[4:5], v[4:5], s[100:101], v[124:125]
	v_pk_fma_f32 v[6:7], v[6:7], s[100:101], v[126:127]
	v_pk_fma_f32 v[0:1], v[0:1], s[100:101], v[254:255]
	v_pk_fma_f32 v[2:3], v[2:3], s[100:101], v[114:115]
	s_waitcnt lgkmcnt(0)
	v_add_f32_e32 v249, v249, v253
	s_and_saveexec_b64 s[98:99], s[2:3]
	global_atomic_add_f32 v[250:251], v249, off offset:640
	s_or_b64 exec, exec, s[98:99]
	v_pk_mul_f32 v[216:217], v[12:13], v[12:13]
	v_pk_mul_f32 v[228:229], v[4:5], v[4:5]
	v_pk_fma_f32 v[216:217], v[14:15], v[14:15], v[216:217]
	v_pk_fma_f32 v[228:229], v[6:7], v[6:7], v[228:229]
	v_pk_fma_f32 v[216:217], v[8:9], v[8:9], v[216:217]
	v_pk_fma_f32 v[228:229], v[0:1], v[0:1], v[228:229]
	v_pk_fma_f32 v[216:217], v[10:11], v[10:11], v[216:217]
	v_pk_fma_f32 v[228:229], v[2:3], v[2:3], v[228:229]
	v_pk_add_f32 v[216:217], v[216:217], v[228:229]
	v_cvt_pk_bf16_f32 v124, v12, v13
	v_cvt_pk_bf16_f32 v125, v14, v15
	v_cvt_pk_bf16_f32 v126, v8, v9
	v_cvt_pk_bf16_f32 v127, v10, v11
	v_lshl_add_u64 v[232:233], v[196:197], 0, s[70:71]
	global_store_dwordx4 v[232:233], v[124:127], off sc1
	v_add_f32_e32 v252, v216, v217
	v_cvt_pk_bf16_f32 v112, v4, v5
	v_cvt_pk_bf16_f32 v113, v6, v7
	v_cvt_pk_bf16_f32 v114, v0, v1
	v_cvt_pk_bf16_f32 v115, v2, v3
	ds_bpermute_b32 v253, v247, v252
	v_lshl_add_u64 v[230:231], v[196:197], 0, s[68:69]
	global_store_dwordx4 v[230:231], v[112:115], off sc1
	s_waitcnt lgkmcnt(0)
	v_add_f32_e32 v252, v252, v253
	ds_bpermute_b32 v253, v248, v252
	s_waitcnt lgkmcnt(0)
	v_add_f32_e32 v252, v252, v253
	s_and_saveexec_b64 s[98:99], s[2:3]
	global_atomic_add_f32 v[250:251], v252, off offset:704
	s_or_b64 exec, exec, s[98:99]
	s_and_b64 vcc, exec, s[4:5]
	s_mov_b64 s[4:5], -1
	s_cbranch_vccnz .LBB0_214
	s_andn2_b64 vcc, exec, s[56:57]
	s_cbranch_vccnz .LBB0_213
	s_barrier
	s_branch .LBB0_213

; __device__ __forceinline__ unsigned cvt_pk_bf16(float lo, float hi) { unsigned r; asm volatile("v_cvt_pk_bf16_f32 %0, %1, %2" : "=v"(r) : "v"(lo), "v"(hi)); return r; }
;     __device__ __forceinline__ char* hb_at(const Unit& u, int ai, int m, int bj, int wr, int wc, int fr, int fq) const {
;         return (char*)hb + ((size_t)((u.pm * 16 + u.pn * 4 + bj * 2 + (wc >> 1)) * 2 + ai) * HTB) + lds_byte(wr * 64 + m * 16 + fr, (wc & 1) * 32 + 8 * fq); }
;     __device__ __forceinline__ void operator()(f32x4 (&acc)[2][2][4][2], const Unit& u, int wr, int wc, int fr, int fq) const {
;         const int row0 = u.pm * BM + wr * 64 + fr, col0 = u.pn * BM + wc * 32 + 8 * fq;
;         u32x4 pre[2][4][2];
; #pragma unroll
;         for (int ai = 0; ai < 2; ++ai)
; #pragma unroll
;             for (int m = 0; m < 4; ++m)
; #pragma unroll
;                 for (int bj = 0; bj < 2; ++bj) pre[ai][m][bj] = *(const u32x4*)hb_at(u, ai, m, bj, wr, wc, fr, fq);
; #pragma unroll
;         for (int ai = 0; ai < 2; ++ai)
; #pragma unroll
;             for (int m = 0; m < 4; ++m) { const int row = row0 + ai * HALF + m * 16; float s = 0.f;
; #pragma unroll
;                 for (int bj = 0; bj < 2; ++bj) { const size_t o2 = (size_t)row * 1024 + col0 + bj * HALF; const u32x4 p = pre[ai][m][bj]; const f32x4 a0 = acc[ai][bj][m][0], a1 = acc[ai][bj][m][1];
;                     f32x4 o0, o1; o0[0] = bf_lo(p.x) + a0[0] * alpha; o0[1] = bf_hi(p.x) + a0[1] * alpha; o0[2] = bf_lo(p.y) + a0[2] * alpha; o0[3] = bf_hi(p.y) + a0[3] * alpha;
;                     o1[0] = bf_lo(p.z) + a1[0] * alpha; o1[1] = bf_hi(p.z) + a1[1] * alpha; o1[2] = bf_lo(p.w) + a1[2] * alpha; o1[3] = bf_hi(p.w) + a1[3] * alpha;
;                     s += ((o0[0] * o0[0] + o0[1] * o0[1]) + (o0[2] * o0[2] + o0[3] * o0[3])) + ((o1[0] * o1[0] + o1[1] * o1[1]) + (o1[2] * o1[2] + o1[3] * o1[3]));
;                     u32x4 w; w.x = cvt_pk_bf16(o0[0], o0[1]); w.y = cvt_pk_bf16(o0[2], o0[3]); w.z = cvt_pk_bf16(o1[0], o1[1]); w.w = cvt_pk_bf16(o1[2], o1[3]);
;                     *(u32x4*)hb_at(u, ai, m, bj, wr, wc, fr, fq) = w;
;                     if (out) { *(f32x4*)(out + o2) = o0; *(f32x4*)(out + o2 + 4) = o1; } }
;                 s += __shfl_xor(s, 16); s += __shfl_xor(s, 32);
;                 if (ssq && fq == 0) atomicAdd(ssq + row, s); }
.LBB0_754:
	s_lshl_b32 s57, s66, 3
	s_lshl_b32 s59, s64, 5
	s_add_i32 s59, s59, s57
	s_or_b32 s66, s59, s77
	s_ashr_i32 s67, s66, 31
	s_lshl_b64 s[68:69], s[66:67], 14
	s_or_b32 s70, s66, 4
	v_lshl_add_u64 v[128:129], v[198:199], 0, s[68:69]
	s_ashr_i32 s71, s70, 31
	global_load_dwordx4 v[220:223], v[128:129], off
	s_lshl_b64 s[70:71], s[70:71], 14
	v_lshl_add_u64 v[128:129], v[198:199], 0, s[70:71]
	global_load_dwordx4 v[224:227], v[128:129], off
	v_lshl_add_u32 v208, s64, 8, v210
	s_or_b32 s64, s66, 1
	s_or_b32 s72, s66, 5
	s_ashr_i32 s65, s64, 31
	s_ashr_i32 s73, s72, 31
	s_lshl_b64 s[66:67], s[64:65], 14
	s_lshl_b64 s[64:65], s[72:73], 14
	v_lshl_add_u64 v[128:129], v[200:201], 0, s[68:69]
	v_lshl_add_u64 v[130:131], v[202:203], 0, s[68:69]
	v_lshl_add_u64 v[132:133], v[196:197], 0, s[68:69]
	v_lshl_add_u64 v[134:135], v[200:201], 0, s[70:71]
	v_lshl_add_u64 v[136:137], v[202:203], 0, s[70:71]
	v_lshl_add_u64 v[138:139], v[196:197], 0, s[70:71]
	v_lshl_add_u64 v[140:141], v[198:199], 0, s[66:67]
	v_lshl_add_u64 v[142:143], v[198:199], 0, s[64:65]
	v_lshl_add_u64 v[144:145], v[200:201], 0, s[66:67]
	v_lshl_add_u64 v[146:147], v[200:201], 0, s[64:65]
	v_lshl_add_u64 v[228:229], v[202:203], 0, s[66:67]
	v_lshl_add_u64 v[230:231], v[202:203], 0, s[64:65]
	v_lshl_add_u64 v[232:233], v[196:197], 0, s[66:67]
	v_lshl_add_u64 v[234:235], v[196:197], 0, s[64:65]
	global_load_dwordx4 v[180:183], v[128:129], off
	global_load_dwordx4 v[176:179], v[134:135], off
	global_load_dwordx4 v[172:175], v[130:131], off
	global_load_dwordx4 v[168:171], v[136:137], off
	global_load_dwordx4 v[164:167], v[132:133], off
	global_load_dwordx4 v[160:163], v[138:139], off
	global_load_dwordx4 v[156:159], v[140:141], off
	global_load_dwordx4 v[152:155], v[142:143], off
	global_load_dwordx4 v[148:151], v[144:145], off
	s_nop 0
	global_load_dwordx4 v[144:147], v[146:147], off
	s_nop 0
	global_load_dwordx4 v[140:143], v[228:229], off
	global_load_dwordx4 v[136:139], v[230:231], off
	global_load_dwordx4 v[132:135], v[232:233], off
	global_load_dwordx4 v[128:131], v[234:235], off
	v_readlane_b32 s99, v246, 6
	s_nop 1
	s_cmp_lt_u32 s99, 4
	s_cbranch_scc0 .Lnoal_5
	s_barrier
.Lnoal_5:
	v_ashrrev_i32_e32 v209, 31, v208
	v_lshl_add_u64 v[250:251], v[208:209], 2, s[0:1]
	v_xor_b32_e32 v247, 16, v216
	v_xor_b32_e32 v248, 32, v216
	v_lshlrev_b32_e32 v247, 2, v247
	v_lshlrev_b32_e32 v248, 2, v248
	s_waitcnt vmcnt(15)
	v_lshlrev_b32_e32 v228, 16, v220
	v_and_b32_e32 v229, 0xffff0000, v220
	v_lshlrev_b32_e32 v230, 16, v221
	v_and_b32_e32 v231, 0xffff0000, v221
	v_lshlrev_b32_e32 v232, 16, v222
	v_and_b32_e32 v233, 0xffff0000, v222
	v_lshlrev_b32_e32 v234, 16, v223
	v_and_b32_e32 v235, 0xffff0000, v223
	v_pk_add_f32 v[124:125], v[124:125], v[228:229]
	v_pk_add_f32 v[126:127], v[126:127], v[230:231]
	v_pk_add_f32 v[120:121], v[120:121], v[232:233]
	v_pk_add_f32 v[122:123], v[122:123], v[234:235]
	s_waitcnt vmcnt(14)
	v_lshlrev_b32_e32 v220, 16, v224
	v_and_b32_e32 v221, 0xffff0000, v224
	v_lshlrev_b32_e32 v222, 16, v225
	v_and_b32_e32 v223, 0xffff0000, v225
	v_lshlrev_b32_e32 v254, 16, v226
	v_and_b32_e32 v255, 0xffff0000, v226
	v_lshlrev_b32_e32 v226, 16, v227
	v_and_b32_e32 v227, 0xffff0000, v227
	v_pk_add_f32 v[116:117], v[116:117], v[220:221]
	v_pk_add_f32 v[118:119], v[118:119], v[222:223]
	v_pk_add_f32 v[112:113], v[112:113], v[254:255]
	v_pk_add_f32 v[114:115], v[114:115], v[226:227]
	v_pk_mul_f32 v[228:229], v[124:125], v[124:125]
	v_pk_mul_f32 v[230:231], v[116:117], v[116:117]
	v_pk_fma_f32 v[228:229], v[126:127], v[126:127], v[228:229]
	v_pk_fma_f32 v[230:231], v[118:119], v[118:119], v[230:231]
	v_pk_fma_f32 v[228:229], v[120:121], v[120:121], v[228:229]
	v_pk_fma_f32 v[230:231], v[112:113], v[112:113], v[230:231]
	v_pk_fma_f32 v[228:229], v[122:123], v[122:123], v[228:229]
	v_pk_fma_f32 v[230:231], v[114:115], v[114:115], v[230:231]
	v_pk_add_f32 v[228:229], v[228:229], v[230:231]
	v_cvt_pk_bf16_f32 v220, v124, v125
	v_cvt_pk_bf16_f32 v221, v126, v127
	v_cvt_pk_bf16_f32 v222, v120, v121
	v_cvt_pk_bf16_f32 v223, v122, v123
	v_lshl_add_u64 v[234:235], v[198:199], 0, s[68:69]
	global_store_dwordx4 v[234:235], v[220:223], off sc1
	v_add_f32_e32 v249, v228, v229
	v_cvt_pk_bf16_f32 v224, v116, v117
	v_cvt_pk_bf16_f32 v225, v118, v119
	v_cvt_pk_bf16_f32 v226, v112, v113
	v_cvt_pk_bf16_f32 v227, v114, v115
	ds_bpermute_b32 v253, v247, v249
	v_lshl_add_u64 v[232:233], v[198:199], 0, s[70:71]
	global_store_dwordx4 v[232:233], v[224:227], off sc1
	s_waitcnt vmcnt(15)
	v_lshlrev_b32_e32 v228, 16, v180
	v_and_b32_e32 v229, 0xffff0000, v180
	v_lshlrev_b32_e32 v230, 16, v181
	v_and_b32_e32 v231, 0xffff0000, v181
	v_lshlrev_b32_e32 v232, 16, v182
	v_and_b32_e32 v233, 0xffff0000, v182
	v_lshlrev_b32_e32 v234, 16, v183
	v_and_b32_e32 v235, 0xffff0000, v183
	v_pk_add_f32 v[108:109], v[108:109], v[228:229]
	v_pk_add_f32 v[110:111], v[110:111], v[230:231]
	v_pk_add_f32 v[104:105], v[104:105], v[232:233]
	v_pk_add_f32 v[106:107], v[106:107], v[234:235]
	s_waitcnt lgkmcnt(0)
	v_add_f32_e32 v249, v249, v253
	ds_bpermute_b32 v253, v248, v249
	s_waitcnt vmcnt(14)
	v_lshlrev_b32_e32 v180, 16, v176
	v_and_b32_e32 v181, 0xffff0000, v176
	v_lshlrev_b32_e32 v182, 16, v177
	v_and_b32_e32 v183, 0xffff0000, v177
	v_lshlrev_b32_e32 v254, 16, v178
	v_and_b32_e32 v255, 0xffff0000, v178
	v_lshlrev_b32_e32 v178, 16, v179
	v_and_b32_e32 v179, 0xffff0000, v179
	v_pk_add_f32 v[100:101], v[100:101], v[180:181]
	v_pk_add_f32 v[102:103], v[102:103], v[182:183]
	v_pk_add_f32 v[96:97], v[96:97], v[254:255]
	v_pk_add_f32 v[98:99], v[98:99], v[178:179]
	s_waitcnt lgkmcnt(0)
; __device__ __forceinline__ unsigned cvt_pk_bf16(float lo, float hi) { unsigned r; asm volatile("v_cvt_pk_bf16_f32 %0, %1, %2" : "=v"(r) : "v"(lo), "v"(hi)); return r; }
; __device__ __forceinline__ float bf_lo(unsigned w) { return __uint_as_float(w << 16); }
; __device__ __forceinline__ float bf_hi(unsigned w) { return __uint_as_float(w & 0xffff0000u); }
;     __device__ __forceinline__ void operator()(f32x4 (&acc)[2][2][4][2], const Unit& u, int wr, int wc, int fr, int fq) const {
;     ...
;             for (int m = 0; m < 4; ++m) { const int row = row0 + ai * HALF + m * 16; float s = 0.f;
; #pragma unroll
;                 for (int bj = 0; bj < 2; ++bj) { const size_t o2 = (size_t)row * 1024 + col0 + bj * HALF; const u32x4 p = pre[ai][m][bj]; const f32x4 a0 = acc[ai][bj][m][0], a1 = acc[ai][bj][m][1];
;                     f32x4 o0, o1; o0[0] = bf_lo(p.x) + a0[0] * alpha; o0[1] = bf_hi(p.x) + a0[1] * alpha; o0[2] = bf_lo(p.y) + a0[2] * alpha; o0[3] = bf_hi(p.y) + a0[3] * alpha;
;                     o1[0] = bf_lo(p.z) + a1[0] * alpha; o1[1] = bf_hi(p.z) + a1[1] * alpha; o1[2] = bf_lo(p.w) + a1[2] * alpha; o1[3] = bf_hi(p.w) + a1[3] * alpha;
;                     s += ((o0[0] * o0[0] + o0[1] * o0[1]) + (o0[2] * o0[2] + o0[3] * o0[3])) + ((o1[0] * o1[0] + o1[1] * o1[1]) + (o1[2] * o1[2] + o1[3] * o1[3]));
;                     u32x4 w; w.x = cvt_pk_bf16(o0[0], o0[1]); w.y = cvt_pk_bf16(o0[2], o0[3]); w.z = cvt_pk_bf16(o1[0], o1[1]); w.w = cvt_pk_bf16(o1[2], o1[3]);
;                     *(u32x4*)hb_at(u, ai, m, bj, wr, wc, fr, fq) = w;
;                     if (out) { *(f32x4*)(out + o2) = o0; *(f32x4*)(out + o2 + 4) = o1; } }
;                 s += __shfl_xor(s, 16); s += __shfl_xor(s, 32);
;                 if (ssq && fq == 0) atomicAdd(ssq + row, s); }
	v_add_f32_e32 v249, v249, v253
	s_and_saveexec_b64 s[98:99], s[2:3]
	global_atomic_add_f32 v[250:251], v249, off
	s_or_b64 exec, exec, s[98:99]
	v_pk_mul_f32 v[228:229], v[108:109], v[108:109]
	v_pk_mul_f32 v[230:231], v[100:101], v[100:101]
	v_pk_fma_f32 v[228:229], v[110:111], v[110:111], v[228:229]
	v_pk_fma_f32 v[230:231], v[102:103], v[102:103], v[230:231]
	v_pk_fma_f32 v[228:229], v[104:105], v[104:105], v[228:229]
	v_pk_fma_f32 v[230:231], v[96:97], v[96:97], v[230:231]
	v_pk_fma_f32 v[228:229], v[106:107], v[106:107], v[228:229]
	v_pk_fma_f32 v[230:231], v[98:99], v[98:99], v[230:231]
	v_pk_add_f32 v[228:229], v[228:229], v[230:231]
	v_cvt_pk_bf16_f32 v180, v108, v109
	v_cvt_pk_bf16_f32 v181, v110, v111
	v_cvt_pk_bf16_f32 v182, v104, v105
	v_cvt_pk_bf16_f32 v183, v106, v107
	v_lshl_add_u64 v[234:235], v[200:201], 0, s[68:69]
	global_store_dwordx4 v[234:235], v[180:183], off sc1
	v_add_f32_e32 v252, v228, v229
	v_cvt_pk_bf16_f32 v176, v100, v101
	v_cvt_pk_bf16_f32 v177, v102, v103
	v_cvt_pk_bf16_f32 v178, v96, v97
	v_cvt_pk_bf16_f32 v179, v98, v99
	ds_bpermute_b32 v253, v247, v252
	v_lshl_add_u64 v[232:233], v[200:201], 0, s[70:71]
	global_store_dwordx4 v[232:233], v[176:179], off sc1
	s_waitcnt vmcnt(15)
	v_lshlrev_b32_e32 v228, 16, v172
	v_and_b32_e32 v229, 0xffff0000, v172
	v_lshlrev_b32_e32 v230, 16, v173
	v_and_b32_e32 v231, 0xffff0000, v173
	v_lshlrev_b32_e32 v232, 16, v174
	v_and_b32_e32 v233, 0xffff0000, v174
	v_lshlrev_b32_e32 v234, 16, v175
	v_and_b32_e32 v235, 0xffff0000, v175
	v_pk_add_f32 v[92:93], v[92:93], v[228:229]
	v_pk_add_f32 v[94:95], v[94:95], v[230:231]
	v_pk_add_f32 v[88:89], v[88:89], v[232:233]
	v_pk_add_f32 v[90:91], v[90:91], v[234:235]
	s_waitcnt lgkmcnt(0)
	v_add_f32_e32 v252, v252, v253
	ds_bpermute_b32 v253, v248, v252
	s_waitcnt vmcnt(14)
	v_lshlrev_b32_e32 v172, 16, v168
	v_and_b32_e32 v173, 0xffff0000, v168
	v_lshlrev_b32_e32 v174, 16, v169
	v_and_b32_e32 v175, 0xffff0000, v169
	v_lshlrev_b32_e32 v254, 16, v170
	v_and_b32_e32 v255, 0xffff0000, v170
	v_lshlrev_b32_e32 v170, 16, v171
	v_and_b32_e32 v171, 0xffff0000, v171
	v_pk_add_f32 v[84:85], v[84:85], v[172:173]
	v_pk_add_f32 v[86:87], v[86:87], v[174:175]
	v_pk_add_f32 v[80:81], v[80:81], v[254:255]
	v_pk_add_f32 v[82:83], v[82:83], v[170:171]
	s_waitcnt lgkmcnt(0)
	v_add_f32_e32 v252, v252, v253
	s_and_saveexec_b64 s[98:99], s[2:3]
	global_atomic_add_f32 v[250:251], v252, off offset:64
	s_or_b64 exec, exec, s[98:99]
	v_pk_mul_f32 v[228:229], v[92:93], v[92:93]
	v_pk_mul_f32 v[230:231], v[84:85], v[84:85]
	v_pk_fma_f32 v[228:229], v[94:95], v[94:95], v[228:229]
	v_pk_fma_f32 v[230:231], v[86:87], v[86:87], v[230:231]
	v_pk_fma_f32 v[228:229], v[88:89], v[88:89], v[228:229]
	v_pk_fma_f32 v[230:231], v[80:81], v[80:81], v[230:231]
	v_pk_fma_f32 v[228:229], v[90:91], v[90:91], v[228:229]
	v_pk_fma_f32 v[230:231], v[82:83], v[82:83], v[230:231]
	v_pk_add_f32 v[228:229], v[228:229], v[230:231]
	v_cvt_pk_bf16_f32 v172, v92, v93
	v_cvt_pk_bf16_f32 v173, v94, v95
	v_cvt_pk_bf16_f32 v174, v88, v89
	v_cvt_pk_bf16_f32 v175, v90, v91
	v_lshl_add_u64 v[234:235], v[202:203], 0, s[68:69]
	global_store_dwordx4 v[234:235], v[172:175], off sc1
	v_add_f32_e32 v249, v228, v229
	v_cvt_pk_bf16_f32 v168, v84, v85
	v_cvt_pk_bf16_f32 v169, v86, v87
	v_cvt_pk_bf16_f32 v170, v80, v81
	v_cvt_pk_bf16_f32 v171, v82, v83
	ds_bpermute_b32 v253, v247, v249
	v_lshl_add_u64 v[232:233], v[202:203], 0, s[70:71]
	global_store_dwordx4 v[232:233], v[168:171], off sc1
	s_waitcnt vmcnt(15)
	v_lshlrev_b32_e32 v228, 16, v164
	v_and_b32_e32 v229, 0xffff0000, v164
	v_lshlrev_b32_e32 v230, 16, v165
	v_and_b32_e32 v231, 0xffff0000, v165
	v_lshlrev_b32_e32 v232, 16, v166
	v_and_b32_e32 v233, 0xffff0000, v166
	v_lshlrev_b32_e32 v234, 16, v167
	v_and_b32_e32 v235, 0xffff0000, v167
	v_pk_add_f32 v[76:77], v[76:77], v[228:229]
	v_pk_add_f32 v[78:79], v[78:79], v[230:231]
	v_pk_add_f32 v[72:73], v[72:73], v[232:233]
	v_pk_add_f32 v[74:75], v[74:75], v[234:235]
	s_waitcnt lgkmcnt(0)
	v_add_f32_e32 v249, v249, v253
	ds_bpermute_b32 v253, v248, v249
	s_waitcnt vmcnt(14)
	v_lshlrev_b32_e32 v164, 16, v160
	v_and_b32_e32 v165, 0xffff0000, v160
	v_lshlrev_b32_e32 v166, 16, v161
	v_and_b32_e32 v167, 0xffff0000, v161
	v_lshlrev_b32_e32 v254, 16, v162
	v_and_b32_e32 v255, 0xffff0000, v162
	v_lshlrev_b32_e32 v162, 16, v163
	v_and_b32_e32 v163, 0xffff0000, v163
	v_pk_add_f32 v[68:69], v[68:69], v[164:165]
	v_pk_add_f32 v[70:71], v[70:71], v[166:167]
	v_pk_add_f32 v[64:65], v[64:65], v[254:255]
	v_pk_add_f32 v[66:67], v[66:67], v[162:163]
	s_waitcnt lgkmcnt(0)
	v_add_f32_e32 v249, v249, v253
	s_and_saveexec_b64 s[98:99], s[2:3]
	global_atomic_add_f32 v[250:251], v249, off offset:128
	s_or_b64 exec, exec, s[98:99]
	v_pk_mul_f32 v[228:229], v[76:77], v[76:77]
	v_pk_mul_f32 v[230:231], v[68:69], v[68:69]
	v_pk_fma_f32 v[228:229], v[78:79], v[78:79], v[228:229]
	v_pk_fma_f32 v[230:231], v[70:71], v[70:71], v[230:231]
	v_pk_fma_f32 v[228:229], v[72:73], v[72:73], v[228:229]
	v_pk_fma_f32 v[230:231], v[64:65], v[64:65], v[230:231]
	v_pk_fma_f32 v[228:229], v[74:75], v[74:75], v[228:229]
	v_pk_fma_f32 v[230:231], v[66:67], v[66:67], v[230:231]
	v_pk_add_f32 v[228:229], v[228:229], v[230:231]
	v_cvt_pk_bf16_f32 v164, v76, v77
	v_cvt_pk_bf16_f32 v165, v78, v79
	v_cvt_pk_bf16_f32 v166, v72, v73
	v_cvt_pk_bf16_f32 v167, v74, v75
	v_lshl_add_u64 v[234:235], v[196:197], 0, s[68:69]
	global_store_dwordx4 v[234:235], v[164:167], off sc1
	v_add_f32_e32 v252, v228, v229
	v_cvt_pk_bf16_f32 v160, v68, v69
	v_cvt_pk_bf16_f32 v161, v70, v71
	v_cvt_pk_bf16_f32 v162, v64, v65
	v_cvt_pk_bf16_f32 v163, v66, v67
	ds_bpermute_b32 v253, v247, v252
	v_lshl_add_u64 v[232:233], v[196:197], 0, s[70:71]
	global_store_dwordx4 v[232:233], v[160:163], off sc1
	s_waitcnt vmcnt(15)
; __device__ __forceinline__ unsigned cvt_pk_bf16(float lo, float hi) { unsigned r; asm volatile("v_cvt_pk_bf16_f32 %0, %1, %2" : "=v"(r) : "v"(lo), "v"(hi)); return r; }
; __device__ __forceinline__ float bf_lo(unsigned w) { return __uint_as_float(w << 16); }
; __device__ __forceinline__ float bf_hi(unsigned w) { return __uint_as_float(w & 0xffff0000u); }
;     __device__ __forceinline__ void operator()(f32x4 (&acc)[2][2][4][2], const Unit& u, int wr, int wc, int fr, int fq) const {
;     ...
;             for (int m = 0; m < 4; ++m) { const int row = row0 + ai * HALF + m * 16; float s = 0.f;
; #pragma unroll
;                 for (int bj = 0; bj < 2; ++bj) { const size_t o2 = (size_t)row * 1024 + col0 + bj * HALF; const u32x4 p = pre[ai][m][bj]; const f32x4 a0 = acc[ai][bj][m][0], a1 = acc[ai][bj][m][1];
;                     f32x4 o0, o1; o0[0] = bf_lo(p.x) + a0[0] * alpha; o0[1] = bf_hi(p.x) + a0[1] * alpha; o0[2] = bf_lo(p.y) + a0[2] * alpha; o0[3] = bf_hi(p.y) + a0[3] * alpha;
;                     o1[0] = bf_lo(p.z) + a1[0] * alpha; o1[1] = bf_hi(p.z) + a1[1] * alpha; o1[2] = bf_lo(p.w) + a1[2] * alpha; o1[3] = bf_hi(p.w) + a1[3] * alpha;
;                     s += ((o0[0] * o0[0] + o0[1] * o0[1]) + (o0[2] * o0[2] + o0[3] * o0[3])) + ((o1[0] * o1[0] + o1[1] * o1[1]) + (o1[2] * o1[2] + o1[3] * o1[3]));
;                     u32x4 w; w.x = cvt_pk_bf16(o0[0], o0[1]); w.y = cvt_pk_bf16(o0[2], o0[3]); w.z = cvt_pk_bf16(o1[0], o1[1]); w.w = cvt_pk_bf16(o1[2], o1[3]);
;                     *(u32x4*)hb_at(u, ai, m, bj, wr, wc, fr, fq) = w;
;                     if (out) { *(f32x4*)(out + o2) = o0; *(f32x4*)(out + o2 + 4) = o1; } }
;                 s += __shfl_xor(s, 16); s += __shfl_xor(s, 32);
;                 if (ssq && fq == 0) atomicAdd(ssq + row, s); }
	v_lshlrev_b32_e32 v228, 16, v156
	v_and_b32_e32 v229, 0xffff0000, v156
	v_lshlrev_b32_e32 v230, 16, v157
	v_and_b32_e32 v231, 0xffff0000, v157
	v_lshlrev_b32_e32 v232, 16, v158
	v_and_b32_e32 v233, 0xffff0000, v158
	v_lshlrev_b32_e32 v234, 16, v159
	v_and_b32_e32 v235, 0xffff0000, v159
	v_pk_add_f32 v[60:61], v[60:61], v[228:229]
	v_pk_add_f32 v[62:63], v[62:63], v[230:231]
	v_pk_add_f32 v[56:57], v[56:57], v[232:233]
	v_pk_add_f32 v[58:59], v[58:59], v[234:235]
	s_waitcnt lgkmcnt(0)
	v_add_f32_e32 v252, v252, v253
	ds_bpermute_b32 v253, v248, v252
	s_waitcnt vmcnt(14)
	v_lshlrev_b32_e32 v156, 16, v152
	v_and_b32_e32 v157, 0xffff0000, v152
	v_lshlrev_b32_e32 v158, 16, v153
	v_and_b32_e32 v159, 0xffff0000, v153
	v_lshlrev_b32_e32 v254, 16, v154
	v_and_b32_e32 v255, 0xffff0000, v154
	v_lshlrev_b32_e32 v154, 16, v155
	v_and_b32_e32 v155, 0xffff0000, v155
	v_pk_add_f32 v[52:53], v[52:53], v[156:157]
	v_pk_add_f32 v[54:55], v[54:55], v[158:159]
	v_pk_add_f32 v[48:49], v[48:49], v[254:255]
	v_pk_add_f32 v[50:51], v[50:51], v[154:155]
	s_waitcnt lgkmcnt(0)
	v_add_f32_e32 v252, v252, v253
	s_and_saveexec_b64 s[98:99], s[2:3]
	global_atomic_add_f32 v[250:251], v252, off offset:192
	s_or_b64 exec, exec, s[98:99]
	v_pk_mul_f32 v[228:229], v[60:61], v[60:61]
	v_pk_mul_f32 v[230:231], v[52:53], v[52:53]
	v_pk_fma_f32 v[228:229], v[62:63], v[62:63], v[228:229]
	v_pk_fma_f32 v[230:231], v[54:55], v[54:55], v[230:231]
	v_pk_fma_f32 v[228:229], v[56:57], v[56:57], v[228:229]
	v_pk_fma_f32 v[230:231], v[48:49], v[48:49], v[230:231]
	v_pk_fma_f32 v[228:229], v[58:59], v[58:59], v[228:229]
	v_pk_fma_f32 v[230:231], v[50:51], v[50:51], v[230:231]
	v_pk_add_f32 v[228:229], v[228:229], v[230:231]
	v_cvt_pk_bf16_f32 v156, v60, v61
	v_cvt_pk_bf16_f32 v157, v62, v63
	v_cvt_pk_bf16_f32 v158, v56, v57
	v_cvt_pk_bf16_f32 v159, v58, v59
	v_lshl_add_u64 v[234:235], v[198:199], 0, s[66:67]
	global_store_dwordx4 v[234:235], v[156:159], off sc1
	v_add_f32_e32 v249, v228, v229
	v_cvt_pk_bf16_f32 v152, v52, v53
	v_cvt_pk_bf16_f32 v153, v54, v55
	v_cvt_pk_bf16_f32 v154, v48, v49
	v_cvt_pk_bf16_f32 v155, v50, v51
	ds_bpermute_b32 v253, v247, v249
	v_lshl_add_u64 v[232:233], v[198:199], 0, s[64:65]
	global_store_dwordx4 v[232:233], v[152:155], off sc1
	s_waitcnt vmcnt(15)
	v_lshlrev_b32_e32 v228, 16, v148
	v_and_b32_e32 v229, 0xffff0000, v148
	v_lshlrev_b32_e32 v230, 16, v149
	v_and_b32_e32 v231, 0xffff0000, v149
	v_lshlrev_b32_e32 v232, 16, v150
	v_and_b32_e32 v233, 0xffff0000, v150
	v_lshlrev_b32_e32 v234, 16, v151
	v_and_b32_e32 v235, 0xffff0000, v151
	v_pk_add_f32 v[44:45], v[44:45], v[228:229]
	v_pk_add_f32 v[46:47], v[46:47], v[230:231]
	v_pk_add_f32 v[40:41], v[40:41], v[232:233]
	v_pk_add_f32 v[42:43], v[42:43], v[234:235]
	s_waitcnt lgkmcnt(0)
	v_add_f32_e32 v249, v249, v253
	ds_bpermute_b32 v253, v248, v249
	s_waitcnt vmcnt(14)
	v_lshlrev_b32_e32 v148, 16, v144
	v_and_b32_e32 v149, 0xffff0000, v144
	v_lshlrev_b32_e32 v150, 16, v145
	v_and_b32_e32 v151, 0xffff0000, v145
	v_lshlrev_b32_e32 v254, 16, v146
	v_and_b32_e32 v255, 0xffff0000, v146
	v_lshlrev_b32_e32 v146, 16, v147
	v_and_b32_e32 v147, 0xffff0000, v147
	v_pk_add_f32 v[36:37], v[36:37], v[148:149]
	v_pk_add_f32 v[38:39], v[38:39], v[150:151]
	v_pk_add_f32 v[32:33], v[32:33], v[254:255]
	v_pk_add_f32 v[34:35], v[34:35], v[146:147]
	s_waitcnt lgkmcnt(0)
	v_add_f32_e32 v249, v249, v253
	s_and_saveexec_b64 s[98:99], s[2:3]
	global_atomic_add_f32 v[250:251], v249, off offset:512
	s_or_b64 exec, exec, s[98:99]
	v_pk_mul_f32 v[228:229], v[44:45], v[44:45]
	v_pk_mul_f32 v[230:231], v[36:37], v[36:37]
	v_pk_fma_f32 v[228:229], v[46:47], v[46:47], v[228:229]
	v_pk_fma_f32 v[230:231], v[38:39], v[38:39], v[230:231]
	v_pk_fma_f32 v[228:229], v[40:41], v[40:41], v[228:229]
	v_pk_fma_f32 v[230:231], v[32:33], v[32:33], v[230:231]
	v_pk_fma_f32 v[228:229], v[42:43], v[42:43], v[228:229]
	v_pk_fma_f32 v[230:231], v[34:35], v[34:35], v[230:231]
	v_pk_add_f32 v[228:229], v[228:229], v[230:231]
	v_cvt_pk_bf16_f32 v148, v44, v45
	v_cvt_pk_bf16_f32 v149, v46, v47
	v_cvt_pk_bf16_f32 v150, v40, v41
	v_cvt_pk_bf16_f32 v151, v42, v43
	v_lshl_add_u64 v[234:235], v[200:201], 0, s[66:67]
	global_store_dwordx4 v[234:235], v[148:151], off sc1
	v_add_f32_e32 v252, v228, v229
	v_cvt_pk_bf16_f32 v144, v36, v37
	v_cvt_pk_bf16_f32 v145, v38, v39
	v_cvt_pk_bf16_f32 v146, v32, v33
	v_cvt_pk_bf16_f32 v147, v34, v35
	ds_bpermute_b32 v253, v247, v252
	v_lshl_add_u64 v[232:233], v[200:201], 0, s[64:65]
	global_store_dwordx4 v[232:233], v[144:147], off sc1
	s_waitcnt vmcnt(15)
; __device__ __forceinline__ unsigned cvt_pk_bf16(float lo, float hi) { unsigned r; asm volatile("v_cvt_pk_bf16_f32 %0, %1, %2" : "=v"(r) : "v"(lo), "v"(hi)); return r; }
; __device__ __forceinline__ float bf_lo(unsigned w) { return __uint_as_float(w << 16); }
; __device__ __forceinline__ float bf_hi(unsigned w) { return __uint_as_float(w & 0xffff0000u); }
;     __device__ __forceinline__ void operator()(f32x4 (&acc)[2][2][4][2], const Unit& u, int wr, int wc, int fr, int fq) const {
;     ...
;             for (int m = 0; m < 4; ++m) { const int row = row0 + ai * HALF + m * 16; float s = 0.f;
; #pragma unroll
;                 for (int bj = 0; bj < 2; ++bj) { const size_t o2 = (size_t)row * 1024 + col0 + bj * HALF; const u32x4 p = pre[ai][m][bj]; const f32x4 a0 = acc[ai][bj][m][0], a1 = acc[ai][bj][m][1];
;                     f32x4 o0, o1; o0[0] = bf_lo(p.x) + a0[0] * alpha; o0[1] = bf_hi(p.x) + a0[1] * alpha; o0[2] = bf_lo(p.y) + a0[2] * alpha; o0[3] = bf_hi(p.y) + a0[3] * alpha;
;                     o1[0] = bf_lo(p.z) + a1[0] * alpha; o1[1] = bf_hi(p.z) + a1[1] * alpha; o1[2] = bf_lo(p.w) + a1[2] * alpha; o1[3] = bf_hi(p.w) + a1[3] * alpha;
;                     s += ((o0[0] * o0[0] + o0[1] * o0[1]) + (o0[2] * o0[2] + o0[3] * o0[3])) + ((o1[0] * o1[0] + o1[1] * o1[1]) + (o1[2] * o1[2] + o1[3] * o1[3]));
;                     u32x4 w; w.x = cvt_pk_bf16(o0[0], o0[1]); w.y = cvt_pk_bf16(o0[2], o0[3]); w.z = cvt_pk_bf16(o1[0], o1[1]); w.w = cvt_pk_bf16(o1[2], o1[3]);
;                     *(u32x4*)hb_at(u, ai, m, bj, wr, wc, fr, fq) = w;
;                     if (out) { *(f32x4*)(out + o2) = o0; *(f32x4*)(out + o2 + 4) = o1; } }
;                 s += __shfl_xor(s, 16); s += __shfl_xor(s, 32);
;                 if (ssq && fq == 0) atomicAdd(ssq + row, s); }
	v_lshlrev_b32_e32 v228, 16, v140
	v_and_b32_e32 v229, 0xffff0000, v140
	v_lshlrev_b32_e32 v230, 16, v141
	v_and_b32_e32 v231, 0xffff0000, v141
	v_lshlrev_b32_e32 v232, 16, v142
	v_and_b32_e32 v233, 0xffff0000, v142
	v_lshlrev_b32_e32 v234, 16, v143
	v_and_b32_e32 v235, 0xffff0000, v143
	v_pk_add_f32 v[28:29], v[28:29], v[228:229]
	v_pk_add_f32 v[30:31], v[30:31], v[230:231]
	v_pk_add_f32 v[24:25], v[24:25], v[232:233]
	v_pk_add_f32 v[26:27], v[26:27], v[234:235]
	s_waitcnt lgkmcnt(0)
	v_add_f32_e32 v252, v252, v253
	ds_bpermute_b32 v253, v248, v252
	s_waitcnt vmcnt(14)
	v_lshlrev_b32_e32 v140, 16, v136
	v_and_b32_e32 v141, 0xffff0000, v136
	v_lshlrev_b32_e32 v142, 16, v137
	v_and_b32_e32 v143, 0xffff0000, v137
	v_lshlrev_b32_e32 v254, 16, v138
	v_and_b32_e32 v255, 0xffff0000, v138
	v_lshlrev_b32_e32 v138, 16, v139
	v_and_b32_e32 v139, 0xffff0000, v139
	v_pk_add_f32 v[20:21], v[20:21], v[140:141]
	v_pk_add_f32 v[22:23], v[22:23], v[142:143]
	v_pk_add_f32 v[16:17], v[16:17], v[254:255]
	v_pk_add_f32 v[18:19], v[18:19], v[138:139]
	s_waitcnt lgkmcnt(0)
	v_add_f32_e32 v252, v252, v253
	s_and_saveexec_b64 s[98:99], s[2:3]
	global_atomic_add_f32 v[250:251], v252, off offset:576
	s_or_b64 exec, exec, s[98:99]
	v_pk_mul_f32 v[228:229], v[28:29], v[28:29]
	v_pk_mul_f32 v[230:231], v[20:21], v[20:21]
	v_pk_fma_f32 v[228:229], v[30:31], v[30:31], v[228:229]
	v_pk_fma_f32 v[230:231], v[22:23], v[22:23], v[230:231]
	v_pk_fma_f32 v[228:229], v[24:25], v[24:25], v[228:229]
	v_pk_fma_f32 v[230:231], v[16:17], v[16:17], v[230:231]
	v_pk_fma_f32 v[228:229], v[26:27], v[26:27], v[228:229]
	v_pk_fma_f32 v[230:231], v[18:19], v[18:19], v[230:231]
	v_pk_add_f32 v[228:229], v[228:229], v[230:231]
	v_cvt_pk_bf16_f32 v140, v28, v29
	v_cvt_pk_bf16_f32 v141, v30, v31
	v_cvt_pk_bf16_f32 v142, v24, v25
	v_cvt_pk_bf16_f32 v143, v26, v27
	v_lshl_add_u64 v[234:235], v[202:203], 0, s[66:67]
	global_store_dwordx4 v[234:235], v[140:143], off sc1
	v_add_f32_e32 v249, v228, v229
	v_cvt_pk_bf16_f32 v136, v20, v21
	v_cvt_pk_bf16_f32 v137, v22, v23
	v_cvt_pk_bf16_f32 v138, v16, v17
	v_cvt_pk_bf16_f32 v139, v18, v19
	ds_bpermute_b32 v253, v247, v249
	v_lshl_add_u64 v[232:233], v[202:203], 0, s[64:65]
	global_store_dwordx4 v[232:233], v[136:139], off sc1
	s_waitcnt vmcnt(15)
	v_lshlrev_b32_e32 v228, 16, v132
	v_and_b32_e32 v229, 0xffff0000, v132
	v_lshlrev_b32_e32 v230, 16, v133
	v_and_b32_e32 v231, 0xffff0000, v133
	v_lshlrev_b32_e32 v232, 16, v134
	v_and_b32_e32 v233, 0xffff0000, v134
	v_lshlrev_b32_e32 v234, 16, v135
	v_and_b32_e32 v235, 0xffff0000, v135
	v_pk_add_f32 v[12:13], v[12:13], v[228:229]
	v_pk_add_f32 v[14:15], v[14:15], v[230:231]
	v_pk_add_f32 v[8:9], v[8:9], v[232:233]
	v_pk_add_f32 v[10:11], v[10:11], v[234:235]
	s_waitcnt lgkmcnt(0)
	v_add_f32_e32 v249, v249, v253
	ds_bpermute_b32 v253, v248, v249
	s_waitcnt vmcnt(14)
	v_lshlrev_b32_e32 v132, 16, v128
	v_and_b32_e32 v133, 0xffff0000, v128
	v_lshlrev_b32_e32 v134, 16, v129
	v_and_b32_e32 v135, 0xffff0000, v129
	v_lshlrev_b32_e32 v254, 16, v130
	v_and_b32_e32 v255, 0xffff0000, v130
	v_lshlrev_b32_e32 v130, 16, v131
	v_and_b32_e32 v131, 0xffff0000, v131
	v_pk_add_f32 v[4:5], v[4:5], v[132:133]
	v_pk_add_f32 v[6:7], v[6:7], v[134:135]
	v_pk_add_f32 v[0:1], v[0:1], v[254:255]
	v_pk_add_f32 v[2:3], v[2:3], v[130:131]
	s_waitcnt lgkmcnt(0)
	v_add_f32_e32 v249, v249, v253
	s_and_saveexec_b64 s[98:99], s[2:3]
	global_atomic_add_f32 v[250:251], v249, off offset:640
	s_or_b64 exec, exec, s[98:99]
	v_pk_mul_f32 v[228:229], v[12:13], v[12:13]
	v_pk_mul_f32 v[230:231], v[4:5], v[4:5]
	v_pk_fma_f32 v[228:229], v[14:15], v[14:15], v[228:229]
	v_pk_fma_f32 v[230:231], v[6:7], v[6:7], v[230:231]
	v_pk_fma_f32 v[228:229], v[8:9], v[8:9], v[228:229]
	v_pk_fma_f32 v[230:231], v[0:1], v[0:1], v[230:231]
	v_pk_fma_f32 v[228:229], v[10:11], v[10:11], v[228:229]
	v_pk_fma_f32 v[230:231], v[2:3], v[2:3], v[230:231]
	v_pk_add_f32 v[228:229], v[228:229], v[230:231]
	v_cvt_pk_bf16_f32 v132, v12, v13
	v_cvt_pk_bf16_f32 v133, v14, v15
	v_cvt_pk_bf16_f32 v134, v8, v9
	v_cvt_pk_bf16_f32 v135, v10, v11
	v_lshl_add_u64 v[234:235], v[196:197], 0, s[66:67]
	global_store_dwordx4 v[234:235], v[132:135], off sc1
	v_add_f32_e32 v252, v228, v229
	v_cvt_pk_bf16_f32 v128, v4, v5
	v_cvt_pk_bf16_f32 v129, v6, v7
	v_cvt_pk_bf16_f32 v130, v0, v1
	v_cvt_pk_bf16_f32 v131, v2, v3
	ds_bpermute_b32 v253, v247, v252
	v_lshl_add_u64 v[232:233], v[196:197], 0, s[64:65]
	global_store_dwordx4 v[232:233], v[128:131], off sc1
	s_waitcnt lgkmcnt(0)
	v_add_f32_e32 v252, v252, v253
	ds_bpermute_b32 v253, v248, v252
	s_waitcnt lgkmcnt(0)
	v_add_f32_e32 v252, v252, v253
	s_and_saveexec_b64 s[98:99], s[2:3]
	global_atomic_add_f32 v[250:251], v252, off offset:704
	s_or_b64 exec, exec, s[98:99]
	s_andn2_b64 vcc, exec, s[4:5]
	s_mov_b64 s[4:5], -1
	s_cbranch_vccnz .LBB0_743
	s_andn2_b64 vcc, exec, s[46:47]
	s_cbranch_vccnz .LBB0_742
	s_barrier
	s_branch .LBB0_742

; __global__ void __launch_bounds__(NTHR, 2) mk_fwd(Args args) {
	.amdhsa_kernel _Z6mk_fwd4Args
		.amdhsa_group_segment_fixed_size 0
		.amdhsa_private_segment_fixed_size 0
		.amdhsa_kernarg_size 408
		.amdhsa_user_sgpr_count 2
		.amdhsa_user_sgpr_dispatch_ptr 0
		.amdhsa_user_sgpr_queue_ptr 0
		.amdhsa_user_sgpr_kernarg_segment_ptr 1
		.amdhsa_user_sgpr_dispatch_id 0
		.amdhsa_user_sgpr_kernarg_preload_length 0
		.amdhsa_user_sgpr_kernarg_preload_offset 0
		.amdhsa_user_sgpr_private_segment_size 0
		.amdhsa_uses_dynamic_stack 0
		.amdhsa_enable_private_segment 0
		.amdhsa_system_sgpr_workgroup_id_x 1
		.amdhsa_system_sgpr_workgroup_id_y 0
		.amdhsa_system_sgpr_workgroup_id_z 0
		.amdhsa_system_sgpr_workgroup_info 0
		.amdhsa_system_vgpr_workitem_id 2
		.amdhsa_next_free_vgpr 256
		.amdhsa_next_free_sgpr 102
		.amdhsa_accum_offset 256
		.amdhsa_reserve_vcc 1
		.amdhsa_float_round_mode_32 0
		.amdhsa_float_round_mode_16_64 0
		.amdhsa_float_denorm_mode_32 3
		.amdhsa_float_denorm_mode_16_64 3
		.amdhsa_dx10_clamp 1
		.amdhsa_ieee_mode 1
		.amdhsa_fp16_overflow 0
		.amdhsa_tg_split 0
		.amdhsa_exception_fp_ieee_invalid_op 0
		.amdhsa_exception_fp_denorm_src 0
		.amdhsa_exception_fp_ieee_div_zero 0
		.amdhsa_exception_fp_ieee_overflow 0
		.amdhsa_exception_fp_ieee_underflow 0
		.amdhsa_exception_fp_ieee_inexact 0
		.amdhsa_exception_int_div_zero 0
	.end_amdhsa_kernel

; __global__ void __launch_bounds__(NTHR, 2) mk_fwd(Args args) {
amdhsa.kernels:
  - .agpr_count:     0
    .args:
      - .offset:         0
        .size:           152
        .value_kind:     by_value
      - .offset:         152
        .size:           4
        .value_kind:     hidden_block_count_x
      - .offset:         156
        .size:           4
        .value_kind:     hidden_block_count_y
      - .offset:         160
        .size:           4
        .value_kind:     hidden_block_count_z
      - .offset:         164
        .size:           2
        .value_kind:     hidden_group_size_x
      - .offset:         166
        .size:           2
        .value_kind:     hidden_group_size_y
      - .offset:         168
        .size:           2
        .value_kind:     hidden_group_size_z
      - .offset:         170
        .size:           2
        .value_kind:     hidden_remainder_x
      - .offset:         172
        .size:           2
        .value_kind:     hidden_remainder_y
      - .offset:         174
        .size:           2
        .value_kind:     hidden_remainder_z
      - .offset:         192
        .size:           8
        .value_kind:     hidden_global_offset_x
      - .offset:         200
        .size:           8
        .value_kind:     hidden_global_offset_y
      - .offset:         208
        .size:           8
        .value_kind:     hidden_global_offset_z
      - .offset:         216
        .size:           2
        .value_kind:     hidden_grid_dims
      - .offset:         240
        .size:           8
        .value_kind:     hidden_multigrid_sync_arg
      - .offset:         272
        .size:           4
        .value_kind:     hidden_dynamic_lds_size
    .group_segment_fixed_size: 0
    .kernarg_segment_align: 8
    .kernarg_segment_size: 408
    .language:       OpenCL C
    .language_version:
      - 2
      - 0
    .max_flat_workgroup_size: 512
    .name:           _Z6mk_fwd4Args
    .private_segment_fixed_size: 0
    .sgpr_count:     108
    .sgpr_spill_count: 12
    .symbol:         _Z6mk_fwd4Args.kd
    .uniform_work_group_size: 1
    .uses_dynamic_stack: false
    .vgpr_count:     256
    .vgpr_spill_count: 0
    .wavefront_size: 64
